# grid barrier: non-leader blocks spin on the global generation word (TOPGEN) instead of their XCC leader's relay word (XGEN[x]); same generation semantics, one atomic + poll round trip fewer on the rel
# baseline (speedup 1.0000x reference)
.LBB0_117:
	s_or_b64 exec, exec, s[8:9]
	v_cvt_f32_u32_e32 v4, v2
	s_waitcnt vmcnt(0)
	v_readfirstlane_b32 s6, v3
	v_rcp_iflag_f32_e32 v4, v4
	s_nop 0
	v_add_u32_e32 v1, s6, v1
	v_add_u32_e32 v5, 1, v1
	v_mul_f32_e32 v3, 0x4f7ffffe, v4
	v_cvt_u32_f32_e32 v3, v3
	v_sub_u32_e32 v4, 0, v2
	v_mul_lo_u32 v4, v4, v3
	v_mul_hi_u32 v4, v3, v4
	v_add_u32_e32 v3, v3, v4
	v_mul_hi_u32 v3, v1, v3
	v_mul_lo_u32 v4, v3, v2
	v_sub_u32_e32 v1, v1, v4
	v_add_u32_e32 v6, 1, v3
	v_cmp_ge_u32_e32 vcc, v1, v2
	v_sub_u32_e32 v4, v1, v2
	s_nop 0
	v_cndmask_b32_e32 v3, v3, v6, vcc
	v_cndmask_b32_e32 v1, v1, v4, vcc
	v_add_u32_e32 v4, 1, v3
	v_cmp_ge_u32_e32 vcc, v1, v2
	s_nop 1
	v_cndmask_b32_e32 v1, v3, v4, vcc
	v_mad_u64_u32 v[2:3], s[6:7], v2, v1, v[2:3]
	v_cmp_ne_u32_e32 vcc, v5, v2
	s_and_saveexec_b64 s[6:7], vcc
	s_xor_b64 s[6:7], exec, s[6:7]
	s_cbranch_execz .LBB0_131
	s_add_u32 s8, s50, 0x3200
	s_addc_u32 s9, s51, 0
	s_mov_b32 s26, 0x400001
	s_mov_b64 s[10:11], 0
	v_mov_b32_e32 v0, 0
	s_branch .LBB0_124

.LBB0_173:
	s_or_b64 exec, exec, s[6:7]
	s_waitcnt vmcnt(0)
	v_readfirstlane_b32 s4, v3
	v_sub_u32_e32 v4, 0, v2
	s_nop 0
	v_add_u32_e32 v3, s4, v1
	v_cvt_f32_u32_e32 v1, v2
	v_rcp_iflag_f32_e32 v1, v1
	s_nop 0
	v_mul_f32_e32 v1, 0x4f7ffffe, v1
	v_cvt_u32_f32_e32 v1, v1
	v_mul_lo_u32 v4, v4, v1
	v_mul_hi_u32 v4, v1, v4
	v_add_u32_e32 v1, v1, v4
	v_mul_hi_u32 v1, v3, v1
	v_mul_lo_u32 v4, v1, v2
	v_sub_u32_e32 v4, v3, v4
	v_cmp_ge_u32_e32 vcc, v4, v2
	v_add_u32_e32 v5, 1, v1
	s_nop 0
	v_cndmask_b32_e32 v1, v1, v5, vcc
	v_sub_u32_e32 v5, v4, v2
	v_cndmask_b32_e32 v4, v4, v5, vcc
	v_cmp_ge_u32_e32 vcc, v4, v2
	v_add_u32_e32 v4, 1, v1
	s_nop 0
	v_cndmask_b32_e32 v1, v1, v4, vcc
	v_add_u32_e32 v4, 1, v3
	v_mad_u64_u32 v[2:3], s[4:5], v2, v1, v[2:3]
	v_cmp_ne_u32_e32 vcc, v4, v2
	s_and_saveexec_b64 s[4:5], vcc
	s_xor_b64 s[4:5], exec, s[4:5]
	s_cbranch_execz .LBB0_187
	s_add_u32 s6, s50, 0x3200
	s_addc_u32 s7, s51, 0
	s_mov_b32 s24, 0x400001
	s_mov_b64 s[8:9], 0
	s_branch .LBB0_180

.LBB0_883:
	s_or_b64 exec, exec, s[6:7]
	s_waitcnt vmcnt(0)
	v_readfirstlane_b32 s4, v3
	v_sub_u32_e32 v4, 0, v2
	s_nop 0
	v_add_u32_e32 v3, s4, v1
	v_cvt_f32_u32_e32 v1, v2
	v_rcp_iflag_f32_e32 v1, v1
	s_nop 0
	v_mul_f32_e32 v1, 0x4f7ffffe, v1
	v_cvt_u32_f32_e32 v1, v1
	v_mul_lo_u32 v4, v4, v1
	v_mul_hi_u32 v4, v1, v4
	v_add_u32_e32 v1, v1, v4
	v_mul_hi_u32 v1, v3, v1
	v_mul_lo_u32 v4, v1, v2
	v_sub_u32_e32 v4, v3, v4
	v_cmp_ge_u32_e32 vcc, v4, v2
	v_add_u32_e32 v5, 1, v1
	s_nop 0
	v_cndmask_b32_e32 v1, v1, v5, vcc
	v_sub_u32_e32 v5, v4, v2
	v_cndmask_b32_e32 v4, v4, v5, vcc
	v_cmp_ge_u32_e32 vcc, v4, v2
	v_add_u32_e32 v4, 1, v1
	s_nop 0
	v_cndmask_b32_e32 v1, v1, v4, vcc
	v_add_u32_e32 v4, 1, v3
	v_mad_u64_u32 v[2:3], s[4:5], v2, v1, v[2:3]
	v_cmp_ne_u32_e32 vcc, v4, v2
	s_and_saveexec_b64 s[4:5], vcc
	s_xor_b64 s[4:5], exec, s[4:5]
	s_cbranch_execz .LBB0_897
	s_add_u32 s6, s50, 0x3200
	s_addc_u32 s7, s51, 0
	s_mov_b32 s25, 0x400001
	s_mov_b64 s[8:9], 0
	s_branch .LBB0_890

.LBB0_938:
	s_or_b64 exec, exec, s[6:7]
	s_waitcnt vmcnt(0)
	v_readfirstlane_b32 s4, v3
	v_sub_u32_e32 v4, 0, v2
	s_nop 0
	v_add_u32_e32 v3, s4, v1
	v_cvt_f32_u32_e32 v1, v2
	v_rcp_iflag_f32_e32 v1, v1
	s_nop 0
	v_mul_f32_e32 v1, 0x4f7ffffe, v1
	v_cvt_u32_f32_e32 v1, v1
	v_mul_lo_u32 v4, v4, v1
	v_mul_hi_u32 v4, v1, v4
	v_add_u32_e32 v1, v1, v4
	v_mul_hi_u32 v1, v3, v1
	v_mul_lo_u32 v4, v1, v2
	v_sub_u32_e32 v4, v3, v4
	v_cmp_ge_u32_e32 vcc, v4, v2
	v_add_u32_e32 v5, 1, v1
	s_nop 0
	v_cndmask_b32_e32 v1, v1, v5, vcc
	v_sub_u32_e32 v5, v4, v2
	v_cndmask_b32_e32 v4, v4, v5, vcc
	v_cmp_ge_u32_e32 vcc, v4, v2
	v_add_u32_e32 v4, 1, v1
	s_nop 0
	v_cndmask_b32_e32 v1, v1, v4, vcc
	v_add_u32_e32 v4, 1, v3
	v_mad_u64_u32 v[2:3], s[4:5], v2, v1, v[2:3]
	v_cmp_ne_u32_e32 vcc, v4, v2
	s_and_saveexec_b64 s[4:5], vcc
	s_xor_b64 s[4:5], exec, s[4:5]
	s_cbranch_execz .LBB0_952
	s_add_u32 s6, s50, 0x3200
	s_addc_u32 s7, s51, 0
	s_mov_b32 s27, 0x400001
	s_mov_b64 s[8:9], 0
	s_branch .LBB0_945
